# Epi3 poll exchanges: no wait for the slot store's completion before the first poll (the poll's own wait covers it)
# speedup vs baseline: 1.0050x; 1.0033x over previous
.LBB0_651:
	s_or_b64 exec, exec, s[0:1]
	s_lshl_b32 s0, s80, 8
	s_or_b32 s0, s0, s58
	v_lshl_add_u32 v190, v3, 3, s0
	v_ashrrev_i32_e32 v3, 31, v2
	v_ashrrev_i32_e32 v189, 31, v188
	v_lshl_add_u64 v[148:149], v[2:3], 0, v[188:189]
	v_ashrrev_i32_e32 v191, 31, v190
	v_readlane_b32 s0, v253, 37
	v_lshlrev_b64 v[148:149], 10, v[148:149]
	v_lshl_add_u64 v[150:151], v[190:191], 0, s[64:65]
	v_readlane_b32 s1, v253, 38
	v_lshl_add_u64 v[194:195], v[150:151], 0, v[148:149]
	v_lshl_add_u64 v[202:203], v[194:195], 1, s[12:13]
	v_lshl_add_u64 v[136:137], v[190:191], 2, s[0:1]
	s_mov_b32 s0, 0x8000
	v_add_co_u32_e32 v148, vcc, s0, v202
	s_mov_b32 s0, 0x10000
	s_nop 0
	v_addc_co_u32_e32 v149, vcc, 0, v203, vcc
	global_load_dwordx4 v[140:143], v[136:137], off offset:16
	global_load_dwordx4 v[144:147], v[136:137], off
	global_load_dwordx4 v[132:135], v[136:137], off offset:528
	s_nop 0
	global_load_dwordx4 v[136:139], v[136:137], off offset:512
	s_nop 0
	global_load_dwordx4 v[160:163], v[202:203], off
	global_load_dwordx4 v[168:171], v[202:203], off offset:256
	global_load_dwordx4 v[172:175], v[148:149], off
	global_load_dwordx4 v[176:179], v[148:149], off offset:256
	v_add_co_u32_e32 v148, vcc, s0, v202
	s_mov_b32 s0, 0x18000
	s_nop 0
	v_addc_co_u32_e32 v149, vcc, 0, v203, vcc
	global_load_dwordx4 v[180:183], v[148:149], off
	global_load_dwordx4 v[164:167], v[148:149], off offset:256
	v_add_co_u32_e32 v148, vcc, s0, v202
	s_ashr_i32 s83, s82, 31
	s_nop 0
	v_addc_co_u32_e32 v149, vcc, 0, v203, vcc
	global_load_dwordx4 v[152:155], v[148:149], off
	s_nop 0
	global_load_dwordx4 v[148:151], v[148:149], off offset:256
	s_lshl_b64 s[0:1], s[82:83], 2
	s_nop 0
	s_add_u32 s2, s49, s0
	s_addc_u32 s3, s60, s1
	s_waitcnt lgkmcnt(0)
	s_mov_b64 s[0:1], exec

.LBB0_770:
	s_or_b64 exec, exec, s[0:1]
	v_readlane_b32 s0, v255, 39
	v_readlane_b32 s1, v255, 40
	s_nop 1
	v_lshl_add_u64 v[136:137], v[190:191], 2, s[0:1]
	global_load_dwordx4 v[140:143], v[136:137], off offset:16
	global_load_dwordx4 v[144:147], v[136:137], off
	global_load_dwordx4 v[132:135], v[136:137], off offset:528
	s_nop 0
	global_load_dwordx4 v[136:139], v[136:137], off offset:512
	s_nop 0
	s_waitcnt lgkmcnt(0)
	s_mov_b64 s[0:1], exec
	s_branch .LBB0_795
